# sample attention: page-table lookups read from an LDS copy (ds_read + lgkmcnt) instead of global_load + vmcnt(0) drains, so the 4 row pieces and 2 tiles of K/V loads stay in flight; on top of v22
# speedup vs baseline: 1.0038x; 1.0038x over previous
.LBB0_2020:
	s_and_b64 vcc, exec, s[4:5]
	s_cbranch_vccz .LBB0_1673
	s_getreg_b32 s3, hwreg(HW_REG_HW_ID, 0, 6)
	s_lshl_b32 s3, s3, 2
	s_add_i32 s3, s3, 0
	s_add_i32 s3, s3, 0x24200
	v_mov_b32_e32 v0, s3
	ds_read_b32 v0, v0
	s_ashr_i32 s8, s2, 2
	s_mov_b32 s6, s8
	v_mov_b32_e32 v5, v1
	v_mov_b32_e32 v6, v1
	s_waitcnt lgkmcnt(0)
	v_readfirstlane_b32 s3, v0
	v_mbcnt_lo_u32_b32 v0, -1, 0
	v_mbcnt_hi_u32_b32 v0, -1, v0
	v_mov_b32_e32 v7, v1
	s_nop 0
	v_lshl_add_u32 v58, s3, 6, v0
	v_cmp_gt_u32_e64 s[100:101], 64, v58
	s_and_saveexec_b64 s[100:101], s[100:101]
	v_lshlrev_b32_e32 v2, 2, v58
	s_lshl_b32 s3, s8, 8
	v_add_u32_e32 v3, s3, v2
	global_load_dword v3, v3, s[84:85]
	v_add_u32_e32 v2, 0x1a800, v2
	s_waitcnt vmcnt(0)
	ds_write_b32 v2, v3
	s_or_b64 exec, exec, s[100:101]
	s_load_dword s4, s[0:1], 0x108
	v_readfirstlane_b32 s3, v58
	s_ashr_i32 s42, s3, 6
	v_readlane_b32 s3, v253, 3
	s_waitcnt lgkmcnt(0)
	s_mov_b64 s[4:5], 0
	s_and_b32 s3, s2, 3
	v_writelane_b32 v254, s3, 3
	s_lshl_b32 s3, s3, 3
	s_add_i32 s4, s42, s3
	s_lshl_b32 s3, s42, 9
	v_writelane_b32 v253, s6, 60
	s_add_i32 s57, s3, 0
	s_mul_i32 s3, s8, 0x2100
	v_writelane_b32 v253, s7, 61
	s_lshl_b32 s5, s4, 7
	v_and_b32_e32 v53, 63, v58
	v_writelane_b32 v253, s5, 45
	s_add_i32 s5, s5, s3
	v_or_b32_e32 v2, s5, v53
	v_readlane_b32 s10, v254, 11
	v_ashrrev_i32_e32 v3, 31, v2
	v_readlane_b32 s11, v254, 12
	v_or_b32_e32 v57, 64, v53
	s_mul_i32 s6, s4, 3
	v_lshl_add_u64 v[2:3], v[2:3], 2, s[10:11]
	global_load_dword v0, v[2:3], off
	v_or_b32_e32 v2, s5, v57
	v_ashrrev_i32_e32 v3, 31, v2
	v_lshl_add_u64 v[2:3], v[2:3], 2, s[10:11]
	global_load_dword v2, v[2:3], off
	s_add_i32 s3, s3, s6
	s_add_i32 s8, s3, 0x2000
	s_ashr_i32 s9, s8, 31
	s_lshl_b64 s[8:9], s[8:9], 2
	s_add_u32 s8, s10, s8
	v_writelane_b32 v253, s5, 46
	v_lshlrev_b32_e32 v59, 2, v53
	s_addc_u32 s9, s11, s9
	s_ashr_i32 s7, s6, 31
	s_lshl_b64 s[6:7], s[6:7], 2
	v_readlane_b32 s3, v253, 58
	s_add_u32 s6, s3, s6
	v_readlane_b32 s3, v254, 10
	s_addc_u32 s7, s3, s7
	global_load_dwordx3 v[50:52], v1, s[8:9]
	global_load_dwordx3 v[54:56], v1, s[6:7]
	s_ashr_i32 s3, s2, 31
	v_ashrrev_i32_e32 v60, 5, v58
	v_and_b32_e32 v48, 31, v58
	s_lshl_b64 s[16:17], s[2:3], 17
	s_movk_i32 s2, 0x1ff
	v_ashrrev_i32_e32 v61, 31, v60
	v_lshlrev_b32_e32 v42, 3, v48
	v_cmp_gt_i32_e64 s[6:7], s2, v60
	s_waitcnt vmcnt(2)
	v_mul_f32_e32 v3, v2, v2
	v_fmac_f32_e32 v3, v0, v0
	ds_swizzle_b32 v4, v3 offset:swizzle(SWAP,1)
	s_waitcnt lgkmcnt(0)
	v_add_f32_e32 v3, v3, v4
	ds_swizzle_b32 v4, v3 offset:swizzle(SWAP,2)
	s_waitcnt lgkmcnt(0)
	v_add_f32_e32 v3, v3, v4
	ds_swizzle_b32 v4, v3 offset:swizzle(SWAP,4)
	s_waitcnt lgkmcnt(0)
	v_add_f32_e32 v3, v3, v4
	ds_swizzle_b32 v4, v3 offset:swizzle(SWAP,8)
	s_waitcnt lgkmcnt(0)
	v_add_f32_e32 v3, v3, v4
	ds_swizzle_b32 v4, v3 offset:swizzle(SWAP,16)
	s_waitcnt lgkmcnt(0)
	v_add_f32_e32 v3, v3, v4
	v_mov_b32_e32 v4, v3
	s_nop 1
	v_permlane32_swap_b32_e32 v3, v4
	v_add_f32_e32 v3, v3, v4
	v_fmamk_f32 v3, v3, 0x3c000000, v163
	v_rsq_f32_e32 v3, v3
	global_load_dword v4, v59, s[92:93]
	v_mul_f32_e32 v3, 0x3db504f3, v3
	v_mul_f32_e32 v0, v0, v3
	v_mul_f32_e32 v2, v2, v3
	global_load_dword v3, v59, s[92:93] offset:256
	s_waitcnt vmcnt(1)
	v_mul_f32_e32 v0, v4, v0
	v_add_u32_e32 v4, s57, v59
	s_waitcnt vmcnt(0)
	v_mul_f32_e32 v2, v3, v2
	ds_write2st64_b32 v4, v0, v2 offset1:1
	v_mov_b32_e32 v0, v1
	v_mov_b32_e32 v2, v1
	v_mov_b32_e32 v3, v1
	v_mov_b32_e32 v4, v1
	v_mov_b64_e32 v[32:33], v[14:15]
	v_mov_b64_e32 v[24:25], v[6:7]
	v_mov_b64_e32 v[22:23], v[4:5]
	v_mov_b64_e32 v[20:21], v[2:3]
	v_mov_b64_e32 v[18:19], v[0:1]
	s_waitcnt lgkmcnt(0)
	s_barrier
	v_mov_b64_e32 v[30:31], v[12:13]
	v_mov_b64_e32 v[28:29], v[10:11]
	v_mov_b64_e32 v[26:27], v[8:9]
	s_mov_b64 s[2:3], exec
	v_writelane_b32 v254, s6, 4
	s_nop 1
	v_writelane_b32 v254, s7, 5
	s_and_b64 s[6:7], s[2:3], s[6:7]
	s_mov_b64 exec, s[6:7]
	s_cbranch_execz .LBB0_2023
	v_readlane_b32 s5, v253, 51
	s_add_u32 s6, s5, s16
	v_readlane_b32 s5, v253, 55
	s_addc_u32 s7, s5, s17
	v_lshlrev_b64 v[2:3], 8, v[60:61]
	v_lshl_add_u64 v[2:3], s[6:7], 0, v[2:3]
	v_mov_b32_e32 v43, v1
	v_lshl_add_u64 v[2:3], v[2:3], 0, v[42:43]
	global_load_dwordx2 v[2:3], v[2:3], off
	v_mov_b32_e32 v22, v1
	v_mov_b32_e32 v23, v1
	v_mov_b32_e32 v24, v1
	v_mov_b32_e32 v25, v1
	s_waitcnt vmcnt(0)
	v_lshlrev_b32_e32 v18, 16, v2
	v_and_b32_e32 v19, 0xffff0000, v2
	v_lshlrev_b32_e32 v20, 16, v3
	v_and_b32_e32 v21, 0xffff0000, v3

.LBB0_2284:
	s_add_i32 s4, s3, 0
	v_add_u32_e32 v14, 0, v0
	v_mov_b32_e32 v6, s4
	v_add_u32_e32 v10, 0x11c00, v14
	v_add_u32_e32 v11, 0x11d00, v14
	ds_read_b128 v[2:5], v6
	ds_read_b128 v[6:9], v6 offset:16
	ds_read_b32 v10, v10
	ds_read_b32 v11, v11
	v_add_u32_e32 v12, 0x11e00, v14
	v_add_u32_e32 v13, 0x11f00, v14
	ds_read_b32 v12, v12
	ds_read_b32 v13, v13
	s_waitcnt lgkmcnt(2)
	v_pk_fma_f32 v[10:11], v[2:3], v[10:11], v[68:69] op_sel_hi:[0,1,1]
	s_add_i32 s3, s3, 32
	s_add_i32 s2, s2, -8
	v_add_u32_e32 v0, 0x1000, v0
	s_waitcnt lgkmcnt(0)
	v_pk_fma_f32 v[2:3], v[2:3], v[12:13], v[10:11] op_sel:[1,0,0]
	v_add_u32_e32 v10, 0x12000, v14
	v_add_u32_e32 v11, 0x12100, v14
	ds_read_b32 v10, v10
	ds_read_b32 v11, v11
	s_cmp_lg_u32 s2, 0
	s_waitcnt lgkmcnt(0)
	v_pk_fma_f32 v[2:3], v[4:5], v[10:11], v[2:3] op_sel_hi:[0,1,1]
	v_add_u32_e32 v4, 0x12200, v14
	ds_read_b32 v10, v4
	v_add_u32_e32 v4, 0x12300, v14
	ds_read_b32 v11, v4
	v_mov_b32_e32 v4, v5
	s_waitcnt lgkmcnt(0)
	v_pk_fma_f32 v[2:3], v[4:5], v[10:11], v[2:3] op_sel_hi:[0,1,1]
	v_add_u32_e32 v4, 0x12400, v14
	v_add_u32_e32 v5, 0x12500, v14
	ds_read_b32 v4, v4
	ds_read_b32 v5, v5
	s_waitcnt lgkmcnt(0)
	v_pk_fma_f32 v[2:3], v[6:7], v[4:5], v[2:3] op_sel_hi:[0,1,1]
	v_add_u32_e32 v4, 0x12600, v14
	v_add_u32_e32 v5, 0x12700, v14
	ds_read_b32 v4, v4
	ds_read_b32 v5, v5
	s_waitcnt lgkmcnt(0)
	v_pk_fma_f32 v[2:3], v[6:7], v[4:5], v[2:3] op_sel:[1,0,0]
	v_add_u32_e32 v4, 0x12800, v14
	v_add_u32_e32 v5, 0x12900, v14
	ds_read_b32 v4, v4
	ds_read_b32 v5, v5
	v_mov_b32_e32 v6, v9
	s_waitcnt lgkmcnt(0)
	v_pk_fma_f32 v[2:3], v[8:9], v[4:5], v[2:3] op_sel_hi:[0,1,1]
	v_add_u32_e32 v4, 0x12a00, v14
	v_add_u32_e32 v5, 0x12b00, v14
	ds_read_b32 v4, v4
	ds_read_b32 v5, v5
	s_waitcnt lgkmcnt(0)
	v_pk_fma_f32 v[68:69], v[6:7], v[4:5], v[2:3] op_sel_hi:[0,1,1]
	s_cbranch_scc1 .LBB0_2284
	v_ashrrev_i32_e32 v0, 11, v58
	v_lshl_add_u32 v0, v0, 2, 0
	v_add_u32_e32 v42, 0x19e10, v0
	s_barrier
	ds_read_b32 v2, v42
	v_readlane_b32 s2, v254, 3
	v_bfe_u32 v38, v58, 5, 6
	s_lshl_b32 s8, s2, 7
	v_readlane_b32 s2, v253, 60
	s_waitcnt lgkmcnt(0)
	v_lshl_or_b32 v0, v2, 6, v38
	v_readlane_b32 s3, v253, 61
	s_lshl_b32 s12, s2, 6
	v_cmp_ne_u32_e32 vcc, s50, v0
	s_and_saveexec_b64 s[2:3], vcc
	s_xor_b64 s[2:3], exec, s[2:3]
	s_cbranch_execz .LBB0_2289
	v_cmp_gt_i32_e32 vcc, s50, v0
	v_mov_b64_e32 v[6:7], 0
	s_and_saveexec_b64 s[4:5], vcc
	s_cbranch_execz .LBB0_2288
	v_ashrrev_i32_e32 v2, 1, v2
	v_lshlrev_b32_e32 v2, 2, v2
	v_add_u32_e32 v2, 0x1a800, v2
	ds_read_b32 v2, v2
	s_nop 0
	v_lshlrev_b32_e32 v0, 12, v0
	v_and_b32_e32 v0, 0x7f000, v0
	s_lshl_b32 s20, s8, 2
	s_waitcnt lgkmcnt(0)
	v_ashrrev_i32_e32 v3, 31, v2
	v_lshlrev_b64 v[2:3], 19, v[2:3]
	v_lshl_add_u64 v[2:3], s[80:81], 0, v[2:3]
	v_lshl_add_u64 v[2:3], v[2:3], 0, v[0:1]
	v_lshl_add_u64 v[6:7], v[2:3], 0, s[20:21]

.LBB0_2293:
	s_or_b64 exec, exec, s[4:5]
	v_ashrrev_i32_e32 v0, 11, v134
	v_lshl_add_u32 v0, v0, 2, 0
	v_add_u32_e32 v43, 0x19e10, v0
	ds_read_b32 v6, v43
	v_bfe_u32 v39, v134, 5, 6
	s_waitcnt lgkmcnt(0)
	v_lshl_or_b32 v0, v6, 6, v39
	v_cmp_ne_u32_e32 vcc, s50, v0
	s_and_saveexec_b64 s[4:5], vcc
	s_xor_b64 s[4:5], exec, s[4:5]
	s_cbranch_execz .LBB0_2297
	v_cmp_gt_i32_e32 vcc, s50, v0
	v_mov_b64_e32 v[10:11], 0
	s_and_saveexec_b64 s[6:7], vcc
	s_cbranch_execz .LBB0_2296
	v_ashrrev_i32_e32 v6, 1, v6
	v_lshlrev_b32_e32 v6, 2, v6
	v_add_u32_e32 v6, 0x1a800, v6
	ds_read_b32 v6, v6
	s_nop 0
	v_lshlrev_b32_e32 v0, 12, v0
	v_and_b32_e32 v0, 0x7f000, v0
	s_lshl_b32 s20, s8, 2
	s_waitcnt lgkmcnt(0)
	v_ashrrev_i32_e32 v7, 31, v6
	v_lshlrev_b64 v[6:7], 19, v[6:7]
	v_lshl_add_u64 v[6:7], s[80:81], 0, v[6:7]
	v_lshl_add_u64 v[6:7], v[6:7], 0, v[0:1]
	v_lshl_add_u64 v[10:11], v[6:7], 0, s[20:21]

.LBB0_2301:
	s_or_b64 exec, exec, s[4:5]
	v_ashrrev_i32_e32 v0, 11, v132
	v_lshl_add_u32 v0, v0, 2, 0
	v_add_u32_e32 v49, 0x19e10, v0
	ds_read_b32 v10, v49
	v_bfe_u32 v40, v132, 5, 6
	s_waitcnt lgkmcnt(0)
	v_lshl_or_b32 v0, v10, 6, v40
	v_cmp_ne_u32_e32 vcc, s50, v0
	s_and_saveexec_b64 s[4:5], vcc
	s_xor_b64 s[4:5], exec, s[4:5]
	s_cbranch_execz .LBB0_2305
	v_cmp_gt_i32_e32 vcc, s50, v0
	v_mov_b64_e32 v[14:15], 0
	s_and_saveexec_b64 s[6:7], vcc
	s_cbranch_execz .LBB0_2304
	v_ashrrev_i32_e32 v10, 1, v10
	v_lshlrev_b32_e32 v10, 2, v10
	v_add_u32_e32 v10, 0x1a800, v10
	ds_read_b32 v10, v10
	s_nop 0
	v_lshlrev_b32_e32 v0, 12, v0
	v_and_b32_e32 v0, 0x7f000, v0
	s_lshl_b32 s20, s8, 2
	s_waitcnt lgkmcnt(0)
	v_ashrrev_i32_e32 v11, 31, v10
	v_lshlrev_b64 v[10:11], 19, v[10:11]
	v_lshl_add_u64 v[10:11], s[80:81], 0, v[10:11]
	v_lshl_add_u64 v[10:11], v[10:11], 0, v[0:1]
	v_lshl_add_u64 v[14:15], v[10:11], 0, s[20:21]

.LBB0_2309:
	s_or_b64 exec, exec, s[4:5]
	v_ashrrev_i32_e32 v0, 11, v133
	v_lshl_add_u32 v0, v0, 2, 0
	v_add_u32_e32 v72, 0x19e10, v0
	ds_read_b32 v16, v72
	v_bfe_u32 v41, v133, 5, 6
	s_waitcnt lgkmcnt(0)
	v_lshl_or_b32 v0, v16, 6, v41
	v_cmp_ne_u32_e32 vcc, s50, v0
	s_and_saveexec_b64 s[4:5], vcc
	s_xor_b64 s[4:5], exec, s[4:5]
	s_cbranch_execz .LBB0_2313
	v_cmp_gt_i32_e32 vcc, s50, v0
	v_mov_b64_e32 v[14:15], 0
	s_and_saveexec_b64 s[6:7], vcc
	s_cbranch_execz .LBB0_2312
	v_ashrrev_i32_e32 v14, 1, v16
	v_lshlrev_b32_e32 v14, 2, v14
	v_add_u32_e32 v14, 0x1a800, v14
	ds_read_b32 v14, v14
	s_nop 0
	v_lshlrev_b32_e32 v0, 12, v0
	v_and_b32_e32 v0, 0x7f000, v0
	s_lshl_b32 s20, s8, 2
	s_waitcnt lgkmcnt(0)
	v_ashrrev_i32_e32 v15, 31, v14
	v_lshlrev_b64 v[14:15], 19, v[14:15]
	v_lshl_add_u64 v[14:15], s[80:81], 0, v[14:15]
	v_lshl_add_u64 v[14:15], v[14:15], 0, v[0:1]
	v_lshl_add_u64 v[14:15], v[14:15], 0, s[20:21]

.LBB0_2317:
	s_or_b64 exec, exec, s[4:5]
	v_add_u32_e32 v74, 64, v60
	v_ashrrev_i32_e32 v0, 6, v74
	v_lshl_add_u32 v0, v0, 2, 0
	v_add_u32_e32 v73, 0x19e10, v0
	ds_read_b32 v14, v73
	s_waitcnt lgkmcnt(0)
	v_lshl_or_b32 v0, v14, 6, v38
	v_cmp_ne_u32_e32 vcc, s50, v0
	s_and_saveexec_b64 s[4:5], vcc
	s_xor_b64 s[4:5], exec, s[4:5]
	s_cbranch_execz .LBB0_2321
	v_cmp_gt_i32_e32 vcc, s50, v0
	v_mov_b64_e32 v[22:23], 0
	s_and_saveexec_b64 s[6:7], vcc
	s_cbranch_execz .LBB0_2320
	v_ashrrev_i32_e32 v14, 1, v14
	v_lshlrev_b32_e32 v14, 2, v14
	v_add_u32_e32 v14, 0x1a800, v14
	ds_read_b32 v14, v14
	s_nop 0
	v_lshlrev_b32_e32 v0, 12, v0
	v_and_b32_e32 v0, 0x7f000, v0
	s_lshl_b32 s20, s8, 2
	s_waitcnt lgkmcnt(0)
	v_ashrrev_i32_e32 v15, 31, v14
	v_lshlrev_b64 v[14:15], 19, v[14:15]
	v_lshl_add_u64 v[14:15], s[80:81], 0, v[14:15]
	v_lshl_add_u64 v[14:15], v[14:15], 0, v[0:1]
	v_lshl_add_u64 v[22:23], v[14:15], 0, s[20:21]

.LBB0_2325:
	s_or_b64 exec, exec, s[4:5]
	v_add_u32_e32 v80, 64, v66
	v_ashrrev_i32_e32 v0, 6, v80
	v_lshl_add_u32 v0, v0, 2, 0
	v_add_u32_e32 v75, 0x19e10, v0
	ds_read_b32 v22, v75
	s_waitcnt lgkmcnt(0)
	v_lshl_or_b32 v0, v22, 6, v39
	v_cmp_ne_u32_e32 vcc, s50, v0
	s_and_saveexec_b64 s[4:5], vcc
	s_xor_b64 s[4:5], exec, s[4:5]
	s_cbranch_execz .LBB0_2329
	v_cmp_gt_i32_e32 vcc, s50, v0
	v_mov_b64_e32 v[26:27], 0
	s_and_saveexec_b64 s[6:7], vcc
	s_cbranch_execz .LBB0_2328
	v_ashrrev_i32_e32 v22, 1, v22
	v_lshlrev_b32_e32 v22, 2, v22
	v_add_u32_e32 v22, 0x1a800, v22
	ds_read_b32 v22, v22
	s_nop 0
	v_lshlrev_b32_e32 v0, 12, v0
	v_and_b32_e32 v0, 0x7f000, v0
	s_lshl_b32 s20, s8, 2
	s_waitcnt lgkmcnt(0)
	v_ashrrev_i32_e32 v23, 31, v22
	v_lshlrev_b64 v[22:23], 19, v[22:23]
	v_lshl_add_u64 v[22:23], s[80:81], 0, v[22:23]
	v_lshl_add_u64 v[22:23], v[22:23], 0, v[0:1]
	v_lshl_add_u64 v[26:27], v[22:23], 0, s[20:21]

.LBB0_2333:
	s_or_b64 exec, exec, s[4:5]
	v_add_u32_e32 v76, 64, v62
	v_ashrrev_i32_e32 v0, 6, v76
	v_lshl_add_u32 v0, v0, 2, 0
	v_add_u32_e32 v77, 0x19e10, v0
	ds_read_b32 v26, v77
	s_waitcnt lgkmcnt(0)
	v_lshl_or_b32 v0, v26, 6, v40
	v_cmp_ne_u32_e32 vcc, s50, v0
	s_and_saveexec_b64 s[4:5], vcc
	s_xor_b64 s[4:5], exec, s[4:5]
	s_cbranch_execz .LBB0_2337
	v_cmp_gt_i32_e32 vcc, s50, v0
	v_mov_b64_e32 v[30:31], 0
	s_and_saveexec_b64 s[6:7], vcc
	s_cbranch_execz .LBB0_2336
	v_ashrrev_i32_e32 v26, 1, v26
	v_lshlrev_b32_e32 v26, 2, v26
	v_add_u32_e32 v26, 0x1a800, v26
	ds_read_b32 v26, v26
	s_nop 0
	v_lshlrev_b32_e32 v0, 12, v0
	v_and_b32_e32 v0, 0x7f000, v0
	s_lshl_b32 s20, s8, 2
	s_waitcnt lgkmcnt(0)
	v_ashrrev_i32_e32 v27, 31, v26
	v_lshlrev_b64 v[26:27], 19, v[26:27]
	v_lshl_add_u64 v[26:27], s[80:81], 0, v[26:27]
	v_lshl_add_u64 v[26:27], v[26:27], 0, v[0:1]
	v_lshl_add_u64 v[30:31], v[26:27], 0, s[20:21]

.LBB0_2341:
	s_or_b64 exec, exec, s[4:5]
	v_add_u32_e32 v78, 64, v64
	v_ashrrev_i32_e32 v0, 6, v78
	v_lshl_add_u32 v0, v0, 2, 0
	v_add_u32_e32 v35, 0x19e10, v0
	ds_read_b32 v30, v35
	s_waitcnt lgkmcnt(0)
	v_lshl_or_b32 v0, v30, 6, v41
	v_cmp_ne_u32_e32 vcc, s50, v0
	s_and_saveexec_b64 s[4:5], vcc
	s_xor_b64 s[4:5], exec, s[4:5]
	s_cbranch_execz .LBB0_2345
	v_cmp_gt_i32_e32 vcc, s50, v0
	v_mov_b64_e32 v[36:37], 0
	s_and_saveexec_b64 s[6:7], vcc
	s_cbranch_execz .LBB0_2344
	v_ashrrev_i32_e32 v30, 1, v30
	v_lshlrev_b32_e32 v30, 2, v30
	v_add_u32_e32 v30, 0x1a800, v30
	ds_read_b32 v30, v30
	s_nop 0
	v_lshlrev_b32_e32 v0, 12, v0
	v_and_b32_e32 v0, 0x7f000, v0
	s_lshl_b32 s20, s8, 2
	s_waitcnt lgkmcnt(0)
	v_ashrrev_i32_e32 v31, 31, v30
	v_lshlrev_b64 v[30:31], 19, v[30:31]
	v_lshl_add_u64 v[30:31], s[80:81], 0, v[30:31]
	v_lshl_add_u64 v[30:31], v[30:31], 0, v[0:1]
	v_lshl_add_u64 v[36:37], v[30:31], 0, s[20:21]

.LBB0_2351:
	global_load_dwordx4 v[84:87], v[82:83], off offset:512
	s_waitcnt vmcnt(1)
	v_pk_mul_f32 v[100:101], v[2:3], v[2:3]
	v_pk_mul_f32 v[88:89], v[18:19], v[18:19]
	v_pk_mul_f32 v[92:93], v[10:11], v[10:11]
	v_pk_mul_f32 v[96:97], v[6:7], v[6:7]
	v_pk_mul_f32 v[98:99], v[4:5], v[4:5]
	v_add_f32_e32 v0, v100, v101
	v_pk_mul_f32 v[36:37], v[20:21], v[20:21]
	v_pk_mul_f32 v[90:91], v[12:13], v[12:13]
	v_pk_mul_f32 v[94:95], v[8:9], v[8:9]
	v_add_f32_e32 v48, v96, v97
	v_add_f32_e32 v71, v92, v93
	v_add_f32_e32 v79, v88, v89
	v_add_f32_e32 v0, v98, v0
	v_add_f32_e32 v48, v94, v48
	v_add_f32_e32 v71, v90, v71
	v_add_f32_e32 v36, v36, v79
	v_add_f32_e32 v0, v99, v0
	v_add_f32_e32 v48, v95, v48
	v_add_f32_e32 v71, v91, v71
	v_add_f32_e32 v36, v37, v36
	ds_swizzle_b32 v37, v0 offset:swizzle(SWAP,1)
	ds_swizzle_b32 v79, v48 offset:swizzle(SWAP,1)
	ds_swizzle_b32 v81, v71 offset:swizzle(SWAP,1)
	ds_swizzle_b32 v88, v36 offset:swizzle(SWAP,1)
	s_add_i32 s13, s18, 2
	s_waitcnt lgkmcnt(3)
	v_add_f32_e32 v0, v0, v37
	s_waitcnt lgkmcnt(2)
	v_add_f32_e32 v37, v48, v79
	s_waitcnt lgkmcnt(1)
	v_add_f32_e32 v48, v71, v81
	ds_swizzle_b32 v71, v0 offset:swizzle(SWAP,2)
	s_waitcnt lgkmcnt(1)
	v_add_f32_e32 v36, v36, v88
	ds_swizzle_b32 v79, v37 offset:swizzle(SWAP,2)
	ds_swizzle_b32 v81, v48 offset:swizzle(SWAP,2)
	ds_swizzle_b32 v88, v36 offset:swizzle(SWAP,2)
	s_waitcnt lgkmcnt(3)
	v_add_f32_e32 v0, v0, v71
	ds_swizzle_b32 v71, v0 offset:swizzle(SWAP,4)
	s_waitcnt lgkmcnt(3)
	v_add_f32_e32 v37, v37, v79
	s_waitcnt lgkmcnt(2)
	v_add_f32_e32 v48, v48, v81
	s_waitcnt lgkmcnt(1)
	v_add_f32_e32 v36, v36, v88
	ds_swizzle_b32 v79, v37 offset:swizzle(SWAP,4)
	ds_swizzle_b32 v81, v48 offset:swizzle(SWAP,4)
	ds_swizzle_b32 v88, v36 offset:swizzle(SWAP,4)
	s_waitcnt lgkmcnt(3)
	v_add_f32_e32 v0, v0, v71
	ds_swizzle_b32 v71, v0 offset:swizzle(SWAP,8)
	s_waitcnt lgkmcnt(3)
	v_add_f32_e32 v37, v37, v79
	s_waitcnt lgkmcnt(2)
	v_add_f32_e32 v48, v48, v81
	s_waitcnt lgkmcnt(1)
	v_add_f32_e32 v36, v36, v88
	ds_swizzle_b32 v79, v37 offset:swizzle(SWAP,8)
	ds_swizzle_b32 v81, v48 offset:swizzle(SWAP,8)
	ds_swizzle_b32 v88, v36 offset:swizzle(SWAP,8)
	s_waitcnt lgkmcnt(3)
	v_add_f32_e32 v0, v0, v71
	ds_swizzle_b32 v71, v0 offset:swizzle(SWAP,16)
	s_waitcnt lgkmcnt(3)
	v_add_f32_e32 v37, v37, v79
	s_waitcnt lgkmcnt(2)
	v_add_f32_e32 v48, v48, v81
	s_waitcnt lgkmcnt(1)
	v_add_f32_e32 v36, v36, v88
	ds_swizzle_b32 v79, v37 offset:swizzle(SWAP,16)
	ds_swizzle_b32 v81, v48 offset:swizzle(SWAP,16)
	ds_swizzle_b32 v88, v36 offset:swizzle(SWAP,16)
	s_waitcnt lgkmcnt(3)
	v_add_f32_e32 v0, v0, v71
	v_fmamk_f32 v0, v0, 0x3c000000, v163
	v_rsq_f32_e32 v0, v0
	s_waitcnt lgkmcnt(2)
	v_add_f32_e32 v37, v37, v79
	s_waitcnt lgkmcnt(1)
	v_add_f32_e32 v48, v48, v81
	s_waitcnt lgkmcnt(0)
	v_add_f32_e32 v71, v36, v88
	v_fmamk_f32 v36, v37, 0x3c000000, v163
	v_fmamk_f32 v37, v48, 0x3c000000, v163
	v_rsq_f32_e32 v36, v36
	v_pk_mul_f32 v[88:89], v[2:3], v[0:1] op_sel_hi:[1,0]
	v_pk_mul_f32 v[90:91], v[4:5], v[0:1] op_sel_hi:[1,0]
	v_fmamk_f32 v0, v71, 0x3c000000, v163
	v_rsq_f32_e32 v48, v37
	v_rsq_f32_e32 v0, v0
	v_add_u32_e32 v138, v44, v34
	v_pk_mul_f32 v[92:93], v[6:7], v[36:37] op_sel_hi:[1,0]
	v_pk_mul_f32 v[36:37], v[8:9], v[36:37] op_sel_hi:[1,0]
	s_cmp_gt_u32 s18, 13
	v_add_u32_e32 v139, v45, v34
	v_pk_mul_f32 v[98:99], v[10:11], v[48:49] op_sel_hi:[1,0]
	v_pk_mul_f32 v[96:97], v[12:13], v[48:49] op_sel_hi:[1,0]
	s_cselect_b64 s[4:5], -1, 0
	s_waitcnt vmcnt(0)
	v_pk_mul_f32 v[90:91], v[86:87], v[90:91]
	v_pk_mul_f32 v[88:89], v[84:85], v[88:89]
	v_pk_mul_f32 v[94:95], v[86:87], v[36:37]
	v_pk_mul_f32 v[92:93], v[84:85], v[92:93]
	ds_write_b128 v138, v[88:91] offset:38912
	ds_write_b128 v139, v[92:95] offset:38912
	v_pk_mul_f32 v[36:37], v[18:19], v[0:1] op_sel_hi:[1,0]
	v_pk_mul_f32 v[88:89], v[20:21], v[0:1] op_sel_hi:[1,0]
	v_pk_mul_f32 v[96:97], v[86:87], v[96:97]
	v_pk_mul_f32 v[94:95], v[84:85], v[98:99]
	v_add_u32_e32 v140, v46, v34
	v_pk_mul_f32 v[86:87], v[86:87], v[88:89]
	v_pk_mul_f32 v[84:85], v[84:85], v[36:37]
	v_add_u32_e32 v141, v47, v34
	s_and_b64 vcc, exec, s[4:5]
	ds_write_b128 v140, v[94:97] offset:38912
	ds_write_b128 v141, v[84:87] offset:38912
	s_waitcnt lgkmcnt(0)
	s_barrier
	s_cbranch_vccnz .LBB0_2377
	s_lshl_b32 s19, s13, 6
	v_add_u32_e32 v0, s19, v60
	v_ashrrev_i32_e32 v0, 6, v0
	v_lshl_add_u32 v0, v0, 2, 0
	v_add_u32_e32 v0, 0x19e10, v0
	ds_read_b32 v2, v0
	v_mov_b64_e32 v[6:7], s[2:3]
	s_waitcnt lgkmcnt(0)
	v_lshl_or_b32 v0, v2, 6, v38
	v_cmp_ne_u32_e32 vcc, s50, v0
	s_and_saveexec_b64 s[6:7], vcc
	s_cbranch_execz .LBB0_2356
	v_cmp_gt_i32_e32 vcc, s50, v0
	v_mov_b64_e32 v[6:7], 0
	s_and_saveexec_b64 s[8:9], vcc
	s_cbranch_execz .LBB0_2355
	v_ashrrev_i32_e32 v2, 1, v2
	v_lshlrev_b32_e32 v2, 2, v2
	v_add_u32_e32 v2, 0x1a800, v2
	ds_read_b32 v2, v2
	s_nop 0
	v_lshlrev_b32_e32 v0, 12, v0
	v_and_b32_e32 v0, 0x7f000, v0
	s_waitcnt lgkmcnt(0)
	v_ashrrev_i32_e32 v3, 31, v2
	v_lshlrev_b64 v[2:3], 19, v[2:3]
	v_lshl_add_u64 v[2:3], s[80:81], 0, v[2:3]
	v_lshl_add_u64 v[2:3], v[2:3], 0, v[0:1]
	v_lshl_add_u64 v[6:7], v[2:3], 0, s[20:21]

.LBB0_2358:
	s_or_b64 exec, exec, s[6:7]
	v_add_u32_e32 v0, s19, v66
	v_ashrrev_i32_e32 v0, 6, v0
	v_lshl_add_u32 v0, v0, 2, 0
	v_add_u32_e32 v0, 0x19e10, v0
	ds_read_b32 v6, v0
	v_mov_b64_e32 v[10:11], s[2:3]
	s_waitcnt lgkmcnt(0)
	v_lshl_or_b32 v0, v6, 6, v39
	v_cmp_ne_u32_e32 vcc, s50, v0
	s_and_saveexec_b64 s[6:7], vcc
	s_cbranch_execz .LBB0_2362
	v_cmp_gt_i32_e32 vcc, s50, v0
	v_mov_b64_e32 v[10:11], 0
	s_and_saveexec_b64 s[8:9], vcc
	s_cbranch_execz .LBB0_2361
	v_ashrrev_i32_e32 v6, 1, v6
	v_lshlrev_b32_e32 v6, 2, v6
	v_add_u32_e32 v6, 0x1a800, v6
	ds_read_b32 v6, v6
	s_nop 0
	v_lshlrev_b32_e32 v0, 12, v0
	v_and_b32_e32 v0, 0x7f000, v0
	s_waitcnt lgkmcnt(0)
	v_ashrrev_i32_e32 v7, 31, v6
	v_lshlrev_b64 v[6:7], 19, v[6:7]
	v_lshl_add_u64 v[6:7], s[80:81], 0, v[6:7]
	v_lshl_add_u64 v[6:7], v[6:7], 0, v[0:1]
	v_lshl_add_u64 v[10:11], v[6:7], 0, s[20:21]

.LBB0_2364:
	s_or_b64 exec, exec, s[6:7]
	v_add_u32_e32 v0, s19, v62
	v_ashrrev_i32_e32 v0, 6, v0
	v_lshl_add_u32 v0, v0, 2, 0
	v_add_u32_e32 v0, 0x19e10, v0
	ds_read_b32 v10, v0
	v_mov_b64_e32 v[18:19], s[2:3]
	s_waitcnt lgkmcnt(0)
	v_lshl_or_b32 v0, v10, 6, v40
	v_cmp_ne_u32_e32 vcc, s50, v0
	s_and_saveexec_b64 s[6:7], vcc
	s_cbranch_execz .LBB0_2368
	v_cmp_gt_i32_e32 vcc, s50, v0
	v_mov_b64_e32 v[18:19], 0
	s_and_saveexec_b64 s[8:9], vcc
	s_cbranch_execz .LBB0_2367
	v_ashrrev_i32_e32 v10, 1, v10
	v_lshlrev_b32_e32 v10, 2, v10
	v_add_u32_e32 v10, 0x1a800, v10
	ds_read_b32 v10, v10
	s_nop 0
	v_lshlrev_b32_e32 v0, 12, v0
	v_and_b32_e32 v0, 0x7f000, v0
	s_waitcnt lgkmcnt(0)
	v_ashrrev_i32_e32 v11, 31, v10
	v_lshlrev_b64 v[10:11], 19, v[10:11]
	v_lshl_add_u64 v[10:11], s[80:81], 0, v[10:11]
	v_lshl_add_u64 v[10:11], v[10:11], 0, v[0:1]
	v_lshl_add_u64 v[18:19], v[10:11], 0, s[20:21]

.LBB0_2370:
	s_or_b64 exec, exec, s[6:7]
	v_add_u32_e32 v0, s19, v64
	v_ashrrev_i32_e32 v0, 6, v0
	v_lshl_add_u32 v0, v0, 2, 0
	v_add_u32_e32 v0, 0x19e10, v0
	ds_read_b32 v18, v0
	v_mov_b64_e32 v[36:37], s[2:3]
	s_waitcnt lgkmcnt(0)
	v_lshl_or_b32 v0, v18, 6, v41
	v_cmp_ne_u32_e32 vcc, s50, v0
	s_and_saveexec_b64 s[6:7], vcc
	s_cbranch_execz .LBB0_2374
	v_cmp_gt_i32_e32 vcc, s50, v0
	v_mov_b64_e32 v[36:37], 0
	s_and_saveexec_b64 s[8:9], vcc
	s_cbranch_execz .LBB0_2373
	v_ashrrev_i32_e32 v18, 1, v18
	v_lshlrev_b32_e32 v18, 2, v18
	v_add_u32_e32 v18, 0x1a800, v18
	ds_read_b32 v18, v18
	s_nop 0
	v_lshlrev_b32_e32 v0, 12, v0
	v_and_b32_e32 v0, 0x7f000, v0
	s_waitcnt lgkmcnt(0)
	v_ashrrev_i32_e32 v19, 31, v18
	v_lshlrev_b64 v[18:19], 19, v[18:19]
	v_lshl_add_u64 v[18:19], s[80:81], 0, v[18:19]
	v_lshl_add_u64 v[18:19], v[18:19], 0, v[0:1]
	v_lshl_add_u64 v[36:37], v[18:19], 0, s[20:21]

.LBB0_2381:
	s_or_b64 exec, exec, s[6:7]
	v_lshl_add_u32 v48, s18, 8, v136
	ds_write_b32 v48, v36 offset:4096
	s_waitcnt lgkmcnt(0)
	s_barrier
	global_load_dwordx4 v[84:87], v[82:83], off offset:512
	v_pk_mul_f32 v[100:101], v[14:15], v[14:15]
	v_pk_mul_f32 v[98:99], v[16:17], v[16:17]
	v_add_f32_e32 v0, v100, v101
	v_pk_mul_f32 v[88:89], v[30:31], v[30:31]
	v_add_f32_e32 v0, v98, v0
	v_pk_mul_f32 v[36:37], v[32:33], v[32:33]
	v_pk_mul_f32 v[96:97], v[22:23], v[22:23]
	v_add_f32_e32 v81, v88, v89
	v_add_f32_e32 v0, v99, v0
	v_pk_mul_f32 v[92:93], v[26:27], v[26:27]
	v_pk_mul_f32 v[94:95], v[24:25], v[24:25]
	v_add_f32_e32 v71, v96, v97
	v_add_f32_e32 v36, v36, v81
	ds_swizzle_b32 v81, v0 offset:swizzle(SWAP,1)
	v_pk_mul_f32 v[90:91], v[28:29], v[28:29]
	v_add_f32_e32 v79, v92, v93
	v_add_f32_e32 v71, v94, v71
	v_add_f32_e32 v79, v90, v79
	v_add_f32_e32 v71, v95, v71
	v_add_f32_e32 v79, v91, v79
	ds_swizzle_b32 v88, v71 offset:swizzle(SWAP,1)
	ds_swizzle_b32 v89, v79 offset:swizzle(SWAP,1)
	v_add_f32_e32 v36, v37, v36
	s_waitcnt lgkmcnt(2)
	v_add_f32_e32 v0, v0, v81
	ds_swizzle_b32 v37, v36 offset:swizzle(SWAP,1)
	ds_swizzle_b32 v81, v0 offset:swizzle(SWAP,2)
	s_waitcnt lgkmcnt(3)
	v_add_f32_e32 v71, v71, v88
	s_waitcnt lgkmcnt(2)
	v_add_f32_e32 v79, v79, v89
	ds_swizzle_b32 v88, v71 offset:swizzle(SWAP,2)
	ds_swizzle_b32 v89, v79 offset:swizzle(SWAP,2)
	s_waitcnt lgkmcnt(3)
	v_add_f32_e32 v36, v36, v37
	s_waitcnt lgkmcnt(2)
	v_add_f32_e32 v0, v0, v81
	ds_swizzle_b32 v37, v36 offset:swizzle(SWAP,2)
	ds_swizzle_b32 v81, v0 offset:swizzle(SWAP,4)
	s_waitcnt lgkmcnt(3)
	v_add_f32_e32 v71, v71, v88
	s_waitcnt lgkmcnt(2)
	v_add_f32_e32 v79, v79, v89
	ds_swizzle_b32 v88, v71 offset:swizzle(SWAP,4)
	ds_swizzle_b32 v89, v79 offset:swizzle(SWAP,4)
	s_waitcnt lgkmcnt(3)
	v_add_f32_e32 v36, v36, v37
	s_waitcnt lgkmcnt(2)
	v_add_f32_e32 v0, v0, v81
	ds_swizzle_b32 v37, v36 offset:swizzle(SWAP,4)
	ds_swizzle_b32 v81, v0 offset:swizzle(SWAP,8)
	s_waitcnt lgkmcnt(3)
	v_add_f32_e32 v71, v71, v88
	s_waitcnt lgkmcnt(2)
	v_add_f32_e32 v79, v79, v89
	ds_swizzle_b32 v88, v71 offset:swizzle(SWAP,8)
	ds_swizzle_b32 v89, v79 offset:swizzle(SWAP,8)
	s_waitcnt lgkmcnt(3)
	v_add_f32_e32 v36, v36, v37
	s_waitcnt lgkmcnt(2)
	v_add_f32_e32 v0, v0, v81
	ds_swizzle_b32 v37, v36 offset:swizzle(SWAP,8)
	ds_swizzle_b32 v81, v0 offset:swizzle(SWAP,16)
	s_waitcnt lgkmcnt(3)
	v_add_f32_e32 v71, v71, v88
	s_waitcnt lgkmcnt(2)
	v_add_f32_e32 v79, v79, v89
	ds_swizzle_b32 v88, v71 offset:swizzle(SWAP,16)
	ds_swizzle_b32 v89, v79 offset:swizzle(SWAP,16)
	s_waitcnt lgkmcnt(3)
	v_add_f32_e32 v97, v36, v37
	s_waitcnt lgkmcnt(2)
	v_add_f32_e32 v0, v0, v81
	ds_swizzle_b32 v100, v97 offset:swizzle(SWAP,16)
	v_fmamk_f32 v0, v0, 0x3c000000, v163
	v_rsq_f32_e32 v0, v0
	s_waitcnt lgkmcnt(2)
	v_add_f32_e32 v36, v71, v88
	s_waitcnt lgkmcnt(1)
	v_add_f32_e32 v37, v79, v89
	v_fmamk_f32 v36, v36, 0x3c000000, v163
	v_fmamk_f32 v37, v37, 0x3c000000, v163
	v_rsq_f32_e32 v36, v36
	v_rsq_f32_e32 v96, v37
	v_pk_mul_f32 v[88:89], v[14:15], v[0:1] op_sel_hi:[1,0]
	v_pk_mul_f32 v[90:91], v[16:17], v[0:1] op_sel_hi:[1,0]
	s_waitcnt lgkmcnt(0)
	v_add_f32_e32 v0, v97, v100
	v_fmamk_f32 v0, v0, 0x3c000000, v163
	v_rsq_f32_e32 v0, v0
	v_pk_mul_f32 v[92:93], v[22:23], v[36:37] op_sel_hi:[1,0]
	v_pk_mul_f32 v[36:37], v[24:25], v[36:37] op_sel_hi:[1,0]
	v_pk_mul_f32 v[98:99], v[26:27], v[96:97] op_sel_hi:[1,0]
	s_lshl_b32 s19, s18, 6
	s_cmp_gt_u32 s18, 12
	s_waitcnt vmcnt(0)
	v_pk_mul_f32 v[90:91], v[86:87], v[90:91]
	v_pk_mul_f32 v[88:89], v[84:85], v[88:89]
	v_pk_mul_f32 v[94:95], v[86:87], v[36:37]
	v_pk_mul_f32 v[36:37], v[28:29], v[96:97] op_sel_hi:[1,0]
	v_pk_mul_f32 v[92:93], v[84:85], v[92:93]
	ds_write_b128 v138, v[88:91] offset:38912
	ds_write_b128 v139, v[92:95] offset:38912
	v_pk_mul_f32 v[90:91], v[86:87], v[36:37]
	v_pk_mul_f32 v[88:89], v[84:85], v[98:99]
	ds_write_b128 v140, v[88:91] offset:38912
	v_pk_mul_f32 v[36:37], v[30:31], v[0:1] op_sel_hi:[1,0]
	v_pk_mul_f32 v[88:89], v[32:33], v[0:1] op_sel_hi:[1,0]
	v_pk_mul_f32 v[84:85], v[84:85], v[36:37]
	v_pk_mul_f32 v[86:87], v[86:87], v[88:89]
	ds_write_b128 v141, v[84:87] offset:38912
	s_waitcnt lgkmcnt(0)
	s_barrier
	s_cbranch_scc1 .LBB0_2407
	s_add_i32 s18, s19, 0xc0
	v_add_u32_e32 v0, s18, v60
	v_ashrrev_i32_e32 v0, 6, v0
	v_lshl_add_u32 v0, v0, 2, 0
	v_add_u32_e32 v0, 0x19e10, v0
	ds_read_b32 v14, v0
	v_mov_b64_e32 v[22:23], s[2:3]
	s_waitcnt lgkmcnt(0)
	v_lshl_or_b32 v0, v14, 6, v38
	v_cmp_ne_u32_e32 vcc, s50, v0
	s_and_saveexec_b64 s[6:7], vcc
	s_cbranch_execz .LBB0_2386
	v_cmp_gt_i32_e32 vcc, s50, v0
	v_mov_b64_e32 v[22:23], 0
	s_and_saveexec_b64 s[8:9], vcc
	s_cbranch_execz .LBB0_2385
	v_ashrrev_i32_e32 v14, 1, v14
	v_lshlrev_b32_e32 v14, 2, v14
	v_add_u32_e32 v14, 0x1a800, v14
	ds_read_b32 v14, v14
	s_nop 0
	v_lshlrev_b32_e32 v0, 12, v0
	v_and_b32_e32 v0, 0x7f000, v0
	s_waitcnt lgkmcnt(0)
	v_ashrrev_i32_e32 v15, 31, v14
	v_lshlrev_b64 v[14:15], 19, v[14:15]
	v_lshl_add_u64 v[14:15], s[80:81], 0, v[14:15]
	v_lshl_add_u64 v[14:15], v[14:15], 0, v[0:1]
	v_lshl_add_u64 v[22:23], v[14:15], 0, s[20:21]

.LBB0_2388:
	s_or_b64 exec, exec, s[6:7]
	v_add_u32_e32 v0, s18, v66
	v_ashrrev_i32_e32 v0, 6, v0
	v_lshl_add_u32 v0, v0, 2, 0
	v_add_u32_e32 v0, 0x19e10, v0
	ds_read_b32 v22, v0
	v_mov_b64_e32 v[26:27], s[2:3]
	s_waitcnt lgkmcnt(0)
	v_lshl_or_b32 v0, v22, 6, v39
	v_cmp_ne_u32_e32 vcc, s50, v0
	s_and_saveexec_b64 s[6:7], vcc
	s_cbranch_execz .LBB0_2392
	v_cmp_gt_i32_e32 vcc, s50, v0
	v_mov_b64_e32 v[26:27], 0
	s_and_saveexec_b64 s[8:9], vcc
	s_cbranch_execz .LBB0_2391
	v_ashrrev_i32_e32 v22, 1, v22
	v_lshlrev_b32_e32 v22, 2, v22
	v_add_u32_e32 v22, 0x1a800, v22
	ds_read_b32 v22, v22
	s_nop 0
	v_lshlrev_b32_e32 v0, 12, v0
	v_and_b32_e32 v0, 0x7f000, v0
	s_waitcnt lgkmcnt(0)
	v_ashrrev_i32_e32 v23, 31, v22
	v_lshlrev_b64 v[22:23], 19, v[22:23]
	v_lshl_add_u64 v[22:23], s[80:81], 0, v[22:23]
	v_lshl_add_u64 v[22:23], v[22:23], 0, v[0:1]
	v_lshl_add_u64 v[26:27], v[22:23], 0, s[20:21]

.LBB0_2394:
	s_or_b64 exec, exec, s[6:7]
	v_add_u32_e32 v0, s18, v62
	v_ashrrev_i32_e32 v0, 6, v0
	v_lshl_add_u32 v0, v0, 2, 0
	v_add_u32_e32 v0, 0x19e10, v0
	ds_read_b32 v26, v0
	v_mov_b64_e32 v[30:31], s[2:3]
	s_waitcnt lgkmcnt(0)
	v_lshl_or_b32 v0, v26, 6, v40
	v_cmp_ne_u32_e32 vcc, s50, v0
	s_and_saveexec_b64 s[6:7], vcc
	s_cbranch_execz .LBB0_2398
	v_cmp_gt_i32_e32 vcc, s50, v0
	v_mov_b64_e32 v[30:31], 0
	s_and_saveexec_b64 s[8:9], vcc
	s_cbranch_execz .LBB0_2397
	v_ashrrev_i32_e32 v26, 1, v26
	v_lshlrev_b32_e32 v26, 2, v26
	v_add_u32_e32 v26, 0x1a800, v26
	ds_read_b32 v26, v26
	s_nop 0
	v_lshlrev_b32_e32 v0, 12, v0
	v_and_b32_e32 v0, 0x7f000, v0
	s_waitcnt lgkmcnt(0)
	v_ashrrev_i32_e32 v27, 31, v26
	v_lshlrev_b64 v[26:27], 19, v[26:27]
	v_lshl_add_u64 v[26:27], s[80:81], 0, v[26:27]
	v_lshl_add_u64 v[26:27], v[26:27], 0, v[0:1]
	v_lshl_add_u64 v[30:31], v[26:27], 0, s[20:21]

.LBB0_2400:
	s_or_b64 exec, exec, s[6:7]
	v_add_u32_e32 v0, s18, v64
	v_ashrrev_i32_e32 v0, 6, v0
	v_lshl_add_u32 v0, v0, 2, 0
	v_add_u32_e32 v0, 0x19e10, v0
	ds_read_b32 v30, v0
	v_mov_b64_e32 v[36:37], s[2:3]
	s_waitcnt lgkmcnt(0)
	v_lshl_or_b32 v0, v30, 6, v41
	v_cmp_ne_u32_e32 vcc, s50, v0
	s_and_saveexec_b64 s[6:7], vcc
	s_cbranch_execz .LBB0_2404
	v_cmp_gt_i32_e32 vcc, s50, v0
	v_mov_b64_e32 v[36:37], 0
	s_and_saveexec_b64 s[8:9], vcc
	s_cbranch_execz .LBB0_2403
	v_ashrrev_i32_e32 v30, 1, v30
	v_lshlrev_b32_e32 v30, 2, v30
	v_add_u32_e32 v30, 0x1a800, v30
	ds_read_b32 v30, v30
	s_nop 0
	v_lshlrev_b32_e32 v0, 12, v0
	v_and_b32_e32 v0, 0x7f000, v0
	s_waitcnt lgkmcnt(0)
	v_ashrrev_i32_e32 v31, 31, v30
	v_lshlrev_b64 v[30:31], 19, v[30:31]
	v_lshl_add_u64 v[30:31], s[80:81], 0, v[30:31]
	v_lshl_add_u64 v[30:31], v[30:31], 0, v[0:1]
	v_lshl_add_u64 v[36:37], v[30:31], 0, s[20:21]

.LBB0_2411:
	ds_read2st64_b32 v[2:3], v136 offset0:16 offset1:17
	ds_read2st64_b32 v[4:5], v136 offset0:18 offset1:19
	ds_read2st64_b32 v[6:7], v136 offset0:20 offset1:21
	ds_read2st64_b32 v[8:9], v136 offset0:22 offset1:23
	s_mov_b32 s2, 0xf149f2ca
	s_waitcnt lgkmcnt(3)
	v_max3_f32 v0, v2, s2, v3
	s_waitcnt lgkmcnt(2)
	v_max3_f32 v0, v0, v4, v5
	s_waitcnt lgkmcnt(1)
	v_max3_f32 v0, v0, v6, v7
	ds_read2st64_b32 v[10:11], v136 offset0:24 offset1:25
	ds_read2st64_b32 v[12:13], v136 offset0:26 offset1:27
	s_waitcnt vmcnt(0)
	ds_read2st64_b32 v[14:15], v136 offset0:28 offset1:29
	ds_read2st64_b32 v[16:17], v136 offset0:30 offset1:31
	s_waitcnt lgkmcnt(4)
	v_max3_f32 v0, v0, v8, v9
	s_waitcnt lgkmcnt(3)
	v_max3_f32 v0, v0, v10, v11
	s_waitcnt lgkmcnt(2)
	v_max3_f32 v0, v0, v12, v13
	s_waitcnt lgkmcnt(1)
	v_max3_f32 v0, v0, v14, v15
	s_waitcnt lgkmcnt(0)
	v_max3_f32 v0, v0, v16, v17
	ds_swizzle_b32 v18, v0 offset:swizzle(SWAP,1)
	s_waitcnt lgkmcnt(0)
	v_max_f32_e32 v18, v18, v18
	v_max_f32_e32 v0, v0, v18
	ds_swizzle_b32 v18, v0 offset:swizzle(SWAP,2)
	s_waitcnt lgkmcnt(0)
	v_max_f32_e32 v18, v18, v18
	v_max_f32_e32 v0, v0, v18
	ds_swizzle_b32 v18, v0 offset:swizzle(SWAP,4)
	s_waitcnt lgkmcnt(0)
	v_max_f32_e32 v18, v18, v18
	v_max_f32_e32 v0, v0, v18
	ds_swizzle_b32 v18, v0 offset:swizzle(SWAP,8)
	s_waitcnt lgkmcnt(0)
	v_max_f32_e32 v18, v18, v18
	v_max_f32_e32 v0, v0, v18
	ds_swizzle_b32 v18, v0 offset:swizzle(SWAP,16)
	s_waitcnt lgkmcnt(0)
	v_max_f32_e32 v18, v18, v18
	v_max_f32_e32 v0, v0, v18
	v_mov_b32_e32 v18, v0
	s_nop 1
	v_permlane32_swap_b32_e32 v0, v18
	v_max_f32_e32 v18, v18, v18
	v_max_f32_e32 v0, v0, v0
	v_max_f32_e32 v0, v0, v18
	v_sub_f32_e32 v2, v2, v0
	v_sub_f32_e32 v3, v3, v0
	v_mul_f32_e32 v2, 0x3fb8aa3b, v2
	v_sub_f32_e32 v4, v4, v0
	v_mul_f32_e32 v3, 0x3fb8aa3b, v3
	v_exp_f32_e32 v2, v2
	v_sub_f32_e32 v5, v5, v0
	v_mul_f32_e32 v4, 0x3fb8aa3b, v4
	v_exp_f32_e32 v3, v3
	v_sub_f32_e32 v6, v6, v0
	v_mul_f32_e32 v5, 0x3fb8aa3b, v5
	v_exp_f32_e32 v4, v4
	v_sub_f32_e32 v7, v7, v0
	v_mul_f32_e32 v6, 0x3fb8aa3b, v6
	v_exp_f32_e32 v5, v5
	v_sub_f32_e32 v8, v8, v0
	v_mul_f32_e32 v7, 0x3fb8aa3b, v7
	v_exp_f32_e32 v6, v6
	v_add_f32_e32 v18, 0, v2
	v_mul_f32_e32 v8, 0x3fb8aa3b, v8
	v_exp_f32_e32 v7, v7
	v_add_f32_e32 v18, v3, v18
	v_sub_f32_e32 v9, v9, v0
	v_exp_f32_e32 v8, v8
	v_add_f32_e32 v18, v4, v18
	v_mul_f32_e32 v9, 0x3fb8aa3b, v9
	v_sub_f32_e32 v10, v10, v0
	v_add_f32_e32 v18, v5, v18
	v_exp_f32_e32 v9, v9
	v_mul_f32_e32 v10, 0x3fb8aa3b, v10
	v_sub_f32_e32 v11, v11, v0
	v_add_f32_e32 v18, v6, v18
	v_exp_f32_e32 v10, v10
	v_mul_f32_e32 v11, 0x3fb8aa3b, v11
	v_sub_f32_e32 v12, v12, v0
	v_add_f32_e32 v18, v7, v18
	v_exp_f32_e32 v11, v11
	v_mul_f32_e32 v12, 0x3fb8aa3b, v12
	v_sub_f32_e32 v13, v13, v0
	v_add_f32_e32 v18, v8, v18
	v_exp_f32_e32 v12, v12
	v_mul_f32_e32 v13, 0x3fb8aa3b, v13
	v_sub_f32_e32 v14, v14, v0
	v_add_f32_e32 v18, v9, v18
	v_exp_f32_e32 v13, v13
	v_mul_f32_e32 v14, 0x3fb8aa3b, v14
	v_sub_f32_e32 v15, v15, v0
	v_add_f32_e32 v18, v10, v18
	v_exp_f32_e32 v14, v14
	v_mul_f32_e32 v15, 0x3fb8aa3b, v15
	v_sub_f32_e32 v16, v16, v0
	v_add_f32_e32 v18, v11, v18
	v_exp_f32_e32 v15, v15
	v_mul_f32_e32 v16, 0x3fb8aa3b, v16
	v_sub_f32_e32 v0, v17, v0
	v_add_f32_e32 v18, v12, v18
	v_exp_f32_e32 v16, v16
	v_mul_f32_e32 v0, 0x3fb8aa3b, v0
	v_add_f32_e32 v18, v13, v18
	v_exp_f32_e32 v0, v0
	v_add_f32_e32 v17, v14, v18
	v_add_f32_e32 v17, v15, v17
	v_add_f32_e32 v17, v16, v17
	v_add_f32_e32 v17, v0, v17
	ds_swizzle_b32 v18, v17 offset:swizzle(SWAP,1)
	s_waitcnt lgkmcnt(0)
	v_add_f32_e32 v17, v17, v18
	ds_swizzle_b32 v18, v17 offset:swizzle(SWAP,2)
	s_waitcnt lgkmcnt(0)
	v_add_f32_e32 v17, v17, v18
	ds_swizzle_b32 v18, v17 offset:swizzle(SWAP,4)
	s_waitcnt lgkmcnt(0)
	v_add_f32_e32 v17, v17, v18
	ds_swizzle_b32 v18, v17 offset:swizzle(SWAP,8)
	s_waitcnt lgkmcnt(0)
	v_add_f32_e32 v17, v17, v18
	ds_swizzle_b32 v18, v17 offset:swizzle(SWAP,16)
	s_waitcnt lgkmcnt(0)
	v_add_f32_e32 v17, v17, v18
	v_mov_b32_e32 v18, v17
	s_nop 1
	v_permlane32_swap_b32_e32 v17, v18
	v_add_f32_e32 v17, v17, v18
	v_rcp_f32_e32 v18, v17
	v_cmp_lt_f32_e32 vcc, 0, v17
	s_nop 1
	v_cndmask_b32_e32 v17, 0, v18, vcc
	v_mul_f32_e32 v2, v2, v17
	v_mul_f32_e32 v3, v3, v17
	ds_write2st64_b32 v136, v2, v3 offset0:16 offset1:17
	v_mul_f32_e32 v2, v4, v17
	v_mul_f32_e32 v3, v5, v17
	ds_write2st64_b32 v136, v2, v3 offset0:18 offset1:19
	v_mul_f32_e32 v2, v6, v17
	v_mul_f32_e32 v3, v7, v17
	ds_write2st64_b32 v136, v2, v3 offset0:20 offset1:21
	v_mul_f32_e32 v2, v8, v17
	v_mul_f32_e32 v3, v9, v17
	ds_write2st64_b32 v136, v2, v3 offset0:22 offset1:23
	v_mul_f32_e32 v2, v10, v17
	v_mul_f32_e32 v3, v11, v17
	ds_write2st64_b32 v136, v2, v3 offset0:24 offset1:25
	v_mul_f32_e32 v2, v12, v17
	v_mul_f32_e32 v3, v13, v17
	ds_write2st64_b32 v136, v2, v3 offset0:26 offset1:27
	v_mul_f32_e32 v2, v14, v17
	v_mul_f32_e32 v3, v15, v17
	ds_write2st64_b32 v136, v2, v3 offset0:28 offset1:29
	v_mul_f32_e32 v2, v16, v17
	v_mul_f32_e32 v0, v0, v17
	ds_write2st64_b32 v136, v2, v0 offset0:30 offset1:31
	s_waitcnt lgkmcnt(0)
	s_barrier
	ds_read_b32 v2, v42
	s_waitcnt lgkmcnt(0)
	v_lshl_or_b32 v0, v2, 6, v38
	v_cmp_ne_u32_e32 vcc, s50, v0
	s_and_saveexec_b64 s[2:3], vcc
	s_xor_b64 s[2:3], exec, s[2:3]
	s_cbranch_execz .LBB0_2415
	v_cmp_gt_i32_e32 vcc, s50, v0
	v_mov_b64_e32 v[6:7], 0
	s_and_saveexec_b64 s[4:5], vcc
	s_cbranch_execz .LBB0_2414
	v_ashrrev_i32_e32 v2, 1, v2
	v_lshlrev_b32_e32 v2, 2, v2
	v_add_u32_e32 v2, 0x1a800, v2
	ds_read_b32 v2, v2
	s_nop 0
	v_lshlrev_b32_e32 v0, 12, v0
	v_and_b32_e32 v0, 0x7f000, v0
	s_mov_b64 s[6:7], 0x800
	s_waitcnt lgkmcnt(0)
	v_ashrrev_i32_e32 v3, 31, v2
	v_lshlrev_b64 v[2:3], 19, v[2:3]
	v_lshl_add_u64 v[2:3], s[80:81], 0, v[2:3]
	v_lshl_add_u64 v[2:3], v[2:3], 0, v[0:1]
	v_lshl_add_u64 v[2:3], v[2:3], 0, s[20:21]
	v_lshl_add_u64 v[6:7], v[2:3], 0, s[6:7]

.LBB0_2419:
	s_or_b64 exec, exec, s[2:3]
	ds_read_b32 v6, v43
	s_waitcnt lgkmcnt(0)
	v_lshl_or_b32 v0, v6, 6, v39
	v_cmp_ne_u32_e32 vcc, s50, v0
	s_and_saveexec_b64 s[2:3], vcc
	s_xor_b64 s[2:3], exec, s[2:3]
	s_cbranch_execz .LBB0_2423
	v_cmp_gt_i32_e32 vcc, s50, v0
	v_mov_b64_e32 v[10:11], 0
	s_and_saveexec_b64 s[4:5], vcc
	s_cbranch_execz .LBB0_2422
	v_ashrrev_i32_e32 v6, 1, v6
	v_lshlrev_b32_e32 v6, 2, v6
	v_add_u32_e32 v6, 0x1a800, v6
	ds_read_b32 v6, v6
	s_nop 0
	v_lshlrev_b32_e32 v0, 12, v0
	v_and_b32_e32 v0, 0x7f000, v0
	s_mov_b64 s[6:7], 0x800
	s_waitcnt lgkmcnt(0)
	v_ashrrev_i32_e32 v7, 31, v6
	v_lshlrev_b64 v[6:7], 19, v[6:7]
	v_lshl_add_u64 v[6:7], s[80:81], 0, v[6:7]
	v_lshl_add_u64 v[6:7], v[6:7], 0, v[0:1]
	v_lshl_add_u64 v[6:7], v[6:7], 0, s[20:21]
	v_lshl_add_u64 v[10:11], v[6:7], 0, s[6:7]

.LBB0_2427:
	s_or_b64 exec, exec, s[2:3]
	ds_read_b32 v10, v49
	s_waitcnt lgkmcnt(0)
	v_lshl_or_b32 v0, v10, 6, v40
	v_cmp_ne_u32_e32 vcc, s50, v0
	s_and_saveexec_b64 s[2:3], vcc
	s_xor_b64 s[2:3], exec, s[2:3]
	s_cbranch_execz .LBB0_2431
	v_cmp_gt_i32_e32 vcc, s50, v0
	v_mov_b64_e32 v[14:15], 0
	s_and_saveexec_b64 s[4:5], vcc
	s_cbranch_execz .LBB0_2430
	v_ashrrev_i32_e32 v10, 1, v10
	v_lshlrev_b32_e32 v10, 2, v10
	v_add_u32_e32 v10, 0x1a800, v10
	ds_read_b32 v10, v10
	s_nop 0
	v_lshlrev_b32_e32 v0, 12, v0
	v_and_b32_e32 v0, 0x7f000, v0
	s_mov_b64 s[6:7], 0x800
	s_waitcnt lgkmcnt(0)
	v_ashrrev_i32_e32 v11, 31, v10
	v_lshlrev_b64 v[10:11], 19, v[10:11]
	v_lshl_add_u64 v[10:11], s[80:81], 0, v[10:11]
	v_lshl_add_u64 v[10:11], v[10:11], 0, v[0:1]
	v_lshl_add_u64 v[10:11], v[10:11], 0, s[20:21]
	v_lshl_add_u64 v[14:15], v[10:11], 0, s[6:7]

.LBB0_2435:
	s_or_b64 exec, exec, s[2:3]
	ds_read_b32 v16, v72
	s_waitcnt lgkmcnt(0)
	v_lshl_or_b32 v0, v16, 6, v41
	v_cmp_ne_u32_e32 vcc, s50, v0
	s_and_saveexec_b64 s[2:3], vcc
	s_xor_b64 s[2:3], exec, s[2:3]
	s_cbranch_execz .LBB0_2439
	v_cmp_gt_i32_e32 vcc, s50, v0
	v_mov_b64_e32 v[14:15], 0
	s_and_saveexec_b64 s[4:5], vcc
	s_cbranch_execz .LBB0_2438
	v_ashrrev_i32_e32 v14, 1, v16
	v_lshlrev_b32_e32 v14, 2, v14
	v_add_u32_e32 v14, 0x1a800, v14
	ds_read_b32 v14, v14
	s_nop 0
	v_lshlrev_b32_e32 v0, 12, v0
	v_and_b32_e32 v0, 0x7f000, v0
	s_mov_b64 s[6:7], 0x800
	s_waitcnt lgkmcnt(0)
	v_ashrrev_i32_e32 v15, 31, v14
	v_lshlrev_b64 v[14:15], 19, v[14:15]
	v_lshl_add_u64 v[14:15], s[80:81], 0, v[14:15]
	v_lshl_add_u64 v[14:15], v[14:15], 0, v[0:1]
	v_lshl_add_u64 v[14:15], v[14:15], 0, s[20:21]
	v_lshl_add_u64 v[14:15], v[14:15], 0, s[6:7]

.LBB0_2443:
	s_or_b64 exec, exec, s[2:3]
	ds_read_b32 v14, v73
	s_waitcnt lgkmcnt(0)
	v_lshl_or_b32 v0, v14, 6, v38
	v_cmp_ne_u32_e32 vcc, s50, v0
	s_and_saveexec_b64 s[2:3], vcc
	s_xor_b64 s[2:3], exec, s[2:3]
	s_cbranch_execz .LBB0_2447
	v_cmp_gt_i32_e32 vcc, s50, v0
	v_mov_b64_e32 v[22:23], 0
	s_and_saveexec_b64 s[4:5], vcc
	s_cbranch_execz .LBB0_2446
	v_ashrrev_i32_e32 v14, 1, v14
	v_lshlrev_b32_e32 v14, 2, v14
	v_add_u32_e32 v14, 0x1a800, v14
	ds_read_b32 v14, v14
	s_nop 0
	v_lshlrev_b32_e32 v0, 12, v0
	v_and_b32_e32 v0, 0x7f000, v0
	s_mov_b64 s[6:7], 0x800
	s_waitcnt lgkmcnt(0)
	v_ashrrev_i32_e32 v15, 31, v14
	v_lshlrev_b64 v[14:15], 19, v[14:15]
	v_lshl_add_u64 v[14:15], s[80:81], 0, v[14:15]
	v_lshl_add_u64 v[14:15], v[14:15], 0, v[0:1]
	v_lshl_add_u64 v[14:15], v[14:15], 0, s[20:21]
	v_lshl_add_u64 v[22:23], v[14:15], 0, s[6:7]

.LBB0_2451:
	s_or_b64 exec, exec, s[2:3]
	ds_read_b32 v22, v75
	s_waitcnt lgkmcnt(0)
	v_lshl_or_b32 v0, v22, 6, v39
	v_cmp_ne_u32_e32 vcc, s50, v0
	s_and_saveexec_b64 s[2:3], vcc
	s_xor_b64 s[2:3], exec, s[2:3]
	s_cbranch_execz .LBB0_2455
	v_cmp_gt_i32_e32 vcc, s50, v0
	v_mov_b64_e32 v[26:27], 0
	s_and_saveexec_b64 s[4:5], vcc
	s_cbranch_execz .LBB0_2454
	v_ashrrev_i32_e32 v22, 1, v22
	v_lshlrev_b32_e32 v22, 2, v22
	v_add_u32_e32 v22, 0x1a800, v22
	ds_read_b32 v22, v22
	s_nop 0
	v_lshlrev_b32_e32 v0, 12, v0
	v_and_b32_e32 v0, 0x7f000, v0
	s_mov_b64 s[6:7], 0x800
	s_waitcnt lgkmcnt(0)
	v_ashrrev_i32_e32 v23, 31, v22
	v_lshlrev_b64 v[22:23], 19, v[22:23]
	v_lshl_add_u64 v[22:23], s[80:81], 0, v[22:23]
	v_lshl_add_u64 v[22:23], v[22:23], 0, v[0:1]
	v_lshl_add_u64 v[22:23], v[22:23], 0, s[20:21]
	v_lshl_add_u64 v[26:27], v[22:23], 0, s[6:7]

.LBB0_2459:
	s_or_b64 exec, exec, s[2:3]
	ds_read_b32 v26, v77
	s_waitcnt lgkmcnt(0)
	v_lshl_or_b32 v0, v26, 6, v40
	v_cmp_ne_u32_e32 vcc, s50, v0
	s_and_saveexec_b64 s[2:3], vcc
	s_xor_b64 s[2:3], exec, s[2:3]
	s_cbranch_execz .LBB0_2463
	v_cmp_gt_i32_e32 vcc, s50, v0
	v_mov_b64_e32 v[30:31], 0
	s_and_saveexec_b64 s[4:5], vcc
	s_cbranch_execz .LBB0_2462
	v_ashrrev_i32_e32 v26, 1, v26
	v_lshlrev_b32_e32 v26, 2, v26
	v_add_u32_e32 v26, 0x1a800, v26
	ds_read_b32 v26, v26
	s_nop 0
	v_lshlrev_b32_e32 v0, 12, v0
	v_and_b32_e32 v0, 0x7f000, v0
	s_mov_b64 s[6:7], 0x800
	s_waitcnt lgkmcnt(0)
	v_ashrrev_i32_e32 v27, 31, v26
	v_lshlrev_b64 v[26:27], 19, v[26:27]
	v_lshl_add_u64 v[26:27], s[80:81], 0, v[26:27]
	v_lshl_add_u64 v[26:27], v[26:27], 0, v[0:1]
	v_lshl_add_u64 v[26:27], v[26:27], 0, s[20:21]
	v_lshl_add_u64 v[30:31], v[26:27], 0, s[6:7]

.LBB0_2467:
	s_or_b64 exec, exec, s[2:3]
	ds_read_b32 v30, v35
	s_waitcnt lgkmcnt(0)
	v_lshl_or_b32 v0, v30, 6, v41
	v_cmp_ne_u32_e32 vcc, s50, v0
	s_and_saveexec_b64 s[2:3], vcc
	s_xor_b64 s[2:3], exec, s[2:3]
	s_cbranch_execz .LBB0_2471
	v_cmp_gt_i32_e32 vcc, s50, v0
	v_mov_b64_e32 v[34:35], 0
	s_and_saveexec_b64 s[4:5], vcc
	s_cbranch_execz .LBB0_2470
	v_ashrrev_i32_e32 v30, 1, v30
	v_lshlrev_b32_e32 v30, 2, v30
	v_add_u32_e32 v30, 0x1a800, v30
	ds_read_b32 v30, v30
	s_nop 0
	v_lshlrev_b32_e32 v0, 12, v0
	v_and_b32_e32 v0, 0x7f000, v0
	s_mov_b64 s[6:7], 0x800
	s_waitcnt lgkmcnt(0)
	v_ashrrev_i32_e32 v31, 31, v30
	v_lshlrev_b64 v[30:31], 19, v[30:31]
	v_lshl_add_u64 v[30:31], s[80:81], 0, v[30:31]
	v_lshl_add_u64 v[30:31], v[30:31], 0, v[0:1]
	v_lshl_add_u64 v[30:31], v[30:31], 0, s[20:21]
	v_lshl_add_u64 v[34:35], v[30:31], 0, s[6:7]

.LBB0_2476:
	s_add_i32 s19, s26, 2
	s_cmp_gt_u32 s26, 13
	s_cselect_b64 s[4:5], -1, 0
	s_and_b64 vcc, exec, s[4:5]
	s_waitcnt vmcnt(0)
	ds_write_b128 v137, v[2:5]
	ds_write_b128 v137, v[6:9] offset:8192
	ds_write_b128 v137, v[10:13] offset:16384
	ds_write_b128 v137, v[18:21] offset:24576
	s_waitcnt lgkmcnt(0)
	s_barrier
	s_cbranch_vccnz .LBB0_2502
	s_lshl_b32 s27, s19, 6
	v_add_u32_e32 v0, s27, v60
	v_ashrrev_i32_e32 v0, 6, v0
	v_lshl_add_u32 v0, v0, 2, 0
	v_add_u32_e32 v0, 0x19e10, v0
	ds_read_b32 v2, v0
	v_mov_b64_e32 v[6:7], s[2:3]
	s_waitcnt lgkmcnt(0)
	v_lshl_or_b32 v0, v2, 6, v38
	v_cmp_ne_u32_e32 vcc, s50, v0
	s_and_saveexec_b64 s[6:7], vcc
	s_cbranch_execz .LBB0_2481
	v_cmp_gt_i32_e32 vcc, s50, v0
	v_mov_b64_e32 v[6:7], 0
	s_and_saveexec_b64 s[8:9], vcc
	s_cbranch_execz .LBB0_2480
	v_ashrrev_i32_e32 v2, 1, v2
	v_lshlrev_b32_e32 v2, 2, v2
	v_add_u32_e32 v2, 0x1a800, v2
	ds_read_b32 v2, v2
	s_nop 0
	v_lshlrev_b32_e32 v0, 12, v0
	v_and_b32_e32 v0, 0x7f000, v0
	s_mov_b64 s[36:37], 0x800
	s_waitcnt lgkmcnt(0)
	v_ashrrev_i32_e32 v3, 31, v2
	v_lshlrev_b64 v[2:3], 19, v[2:3]
	v_lshl_add_u64 v[2:3], s[80:81], 0, v[2:3]
	v_lshl_add_u64 v[2:3], v[2:3], 0, v[0:1]
	v_lshl_add_u64 v[2:3], v[2:3], 0, s[20:21]
	v_lshl_add_u64 v[6:7], v[2:3], 0, s[36:37]

.LBB0_2483:
	s_or_b64 exec, exec, s[6:7]
	v_add_u32_e32 v0, s27, v66
	v_ashrrev_i32_e32 v0, 6, v0
	v_lshl_add_u32 v0, v0, 2, 0
	v_add_u32_e32 v0, 0x19e10, v0
	ds_read_b32 v6, v0
	v_mov_b64_e32 v[10:11], s[2:3]
	s_waitcnt lgkmcnt(0)
	v_lshl_or_b32 v0, v6, 6, v39
	v_cmp_ne_u32_e32 vcc, s50, v0
	s_and_saveexec_b64 s[6:7], vcc
	s_cbranch_execz .LBB0_2487
	v_cmp_gt_i32_e32 vcc, s50, v0
	v_mov_b64_e32 v[10:11], 0
	s_and_saveexec_b64 s[8:9], vcc
	s_cbranch_execz .LBB0_2486
	v_ashrrev_i32_e32 v6, 1, v6
	v_lshlrev_b32_e32 v6, 2, v6
	v_add_u32_e32 v6, 0x1a800, v6
	ds_read_b32 v6, v6
	s_nop 0
	v_lshlrev_b32_e32 v0, 12, v0
	v_and_b32_e32 v0, 0x7f000, v0
	s_mov_b64 s[36:37], 0x800
	s_waitcnt lgkmcnt(0)
	v_ashrrev_i32_e32 v7, 31, v6
	v_lshlrev_b64 v[6:7], 19, v[6:7]
	v_lshl_add_u64 v[6:7], s[80:81], 0, v[6:7]
	v_lshl_add_u64 v[6:7], v[6:7], 0, v[0:1]
	v_lshl_add_u64 v[6:7], v[6:7], 0, s[20:21]
	v_lshl_add_u64 v[10:11], v[6:7], 0, s[36:37]

.LBB0_2489:
	s_or_b64 exec, exec, s[6:7]
	v_add_u32_e32 v0, s27, v62
	v_ashrrev_i32_e32 v0, 6, v0
	v_lshl_add_u32 v0, v0, 2, 0
	v_add_u32_e32 v0, 0x19e10, v0
	ds_read_b32 v10, v0
	v_mov_b64_e32 v[18:19], s[2:3]
	s_waitcnt lgkmcnt(0)
	v_lshl_or_b32 v0, v10, 6, v40
	v_cmp_ne_u32_e32 vcc, s50, v0
	s_and_saveexec_b64 s[6:7], vcc
	s_cbranch_execz .LBB0_2493
	v_cmp_gt_i32_e32 vcc, s50, v0
	v_mov_b64_e32 v[18:19], 0
	s_and_saveexec_b64 s[8:9], vcc
	s_cbranch_execz .LBB0_2492
	v_ashrrev_i32_e32 v10, 1, v10
	v_lshlrev_b32_e32 v10, 2, v10
	v_add_u32_e32 v10, 0x1a800, v10
	ds_read_b32 v10, v10
	s_nop 0
	v_lshlrev_b32_e32 v0, 12, v0
	v_and_b32_e32 v0, 0x7f000, v0
	s_mov_b64 s[36:37], 0x800
	s_waitcnt lgkmcnt(0)
	v_ashrrev_i32_e32 v11, 31, v10
	v_lshlrev_b64 v[10:11], 19, v[10:11]
	v_lshl_add_u64 v[10:11], s[80:81], 0, v[10:11]
	v_lshl_add_u64 v[10:11], v[10:11], 0, v[0:1]
	v_lshl_add_u64 v[10:11], v[10:11], 0, s[20:21]
	v_lshl_add_u64 v[18:19], v[10:11], 0, s[36:37]

.LBB0_2495:
	s_or_b64 exec, exec, s[6:7]
	v_add_u32_e32 v0, s27, v64
	v_ashrrev_i32_e32 v0, 6, v0
	v_lshl_add_u32 v0, v0, 2, 0
	v_add_u32_e32 v0, 0x19e10, v0
	ds_read_b32 v18, v0
	v_mov_b64_e32 v[34:35], s[2:3]
	s_waitcnt lgkmcnt(0)
	v_lshl_or_b32 v0, v18, 6, v41
	v_cmp_ne_u32_e32 vcc, s50, v0
	s_and_saveexec_b64 s[6:7], vcc
	s_cbranch_execz .LBB0_2499
	v_cmp_gt_i32_e32 vcc, s50, v0
	v_mov_b64_e32 v[34:35], 0
	s_and_saveexec_b64 s[8:9], vcc
	s_cbranch_execz .LBB0_2498
	v_ashrrev_i32_e32 v18, 1, v18
	v_lshlrev_b32_e32 v18, 2, v18
	v_add_u32_e32 v18, 0x1a800, v18
	ds_read_b32 v18, v18
	s_nop 0
	v_lshlrev_b32_e32 v0, 12, v0
	v_and_b32_e32 v0, 0x7f000, v0
	s_mov_b64 s[36:37], 0x800
	s_waitcnt lgkmcnt(0)
	v_ashrrev_i32_e32 v19, 31, v18
	v_lshlrev_b64 v[18:19], 19, v[18:19]
	v_lshl_add_u64 v[18:19], s[80:81], 0, v[18:19]
	v_lshl_add_u64 v[18:19], v[18:19], 0, v[0:1]
	v_lshl_add_u64 v[18:19], v[18:19], 0, s[20:21]
	v_lshl_add_u64 v[34:35], v[18:19], 0, s[36:37]

.LBB0_2503:
	s_add_i32 s8, s7, 0
	v_add_u32_e32 v71, 0, v0
	v_mov_b32_e32 v42, s8
	v_add_u32_e32 v46, 0x11c00, v71
	v_add_u32_e32 v47, 0x11d00, v71
	ds_read_b128 v[34:37], v42
	ds_read_b128 v[42:45], v42 offset:16
	ds_read_b32 v46, v46
	ds_read_b32 v47, v47
	v_add_u32_e32 v48, 0x11e00, v71
	v_add_u32_e32 v49, 0x11f00, v71
	ds_read_b32 v48, v48
	ds_read_b32 v49, v49
	s_waitcnt lgkmcnt(2)
	v_pk_fma_f32 v[46:47], v[34:35], v[46:47], v[72:73] op_sel_hi:[0,1,1]
	s_add_i32 s7, s7, 32
	s_add_i32 s6, s6, -8
	v_add_u32_e32 v0, 0x1000, v0
	s_waitcnt lgkmcnt(0)
	v_pk_fma_f32 v[34:35], v[34:35], v[48:49], v[46:47] op_sel:[1,0,0]
	v_add_u32_e32 v46, 0x12000, v71
	v_add_u32_e32 v47, 0x12100, v71
	ds_read_b32 v46, v46
	ds_read_b32 v47, v47
	s_cmp_eq_u32 s6, 0
	s_waitcnt lgkmcnt(0)
	v_pk_fma_f32 v[34:35], v[36:37], v[46:47], v[34:35] op_sel_hi:[0,1,1]
	v_add_u32_e32 v36, 0x12200, v71
	ds_read_b32 v46, v36
	v_add_u32_e32 v36, 0x12300, v71
	ds_read_b32 v47, v36
	v_mov_b32_e32 v36, v37
	s_waitcnt lgkmcnt(0)
	v_pk_fma_f32 v[34:35], v[36:37], v[46:47], v[34:35] op_sel_hi:[0,1,1]
	v_add_u32_e32 v36, 0x12400, v71
	v_add_u32_e32 v37, 0x12500, v71
	ds_read_b32 v36, v36
	ds_read_b32 v37, v37
	s_waitcnt lgkmcnt(0)
	v_pk_fma_f32 v[34:35], v[42:43], v[36:37], v[34:35] op_sel_hi:[0,1,1]
	v_add_u32_e32 v36, 0x12600, v71
	v_add_u32_e32 v37, 0x12700, v71
	ds_read_b32 v36, v36
	ds_read_b32 v37, v37
	s_waitcnt lgkmcnt(0)
	v_pk_fma_f32 v[34:35], v[42:43], v[36:37], v[34:35] op_sel:[1,0,0]
	v_add_u32_e32 v36, 0x12800, v71
	v_add_u32_e32 v37, 0x12900, v71
	ds_read_b32 v36, v36
	ds_read_b32 v37, v37
	v_mov_b32_e32 v42, v45
	s_waitcnt lgkmcnt(0)
	v_pk_fma_f32 v[34:35], v[44:45], v[36:37], v[34:35] op_sel_hi:[0,1,1]
	v_add_u32_e32 v36, 0x12a00, v71
	v_add_u32_e32 v37, 0x12b00, v71
	ds_read_b32 v36, v36
	ds_read_b32 v37, v37
	s_waitcnt lgkmcnt(0)
	v_pk_fma_f32 v[72:73], v[42:43], v[36:37], v[34:35] op_sel_hi:[0,1,1]
	s_cbranch_scc0 .LBB0_2503
	s_cmp_lt_u32 s26, 13
	s_barrier
	ds_write_b128 v137, v[14:17]
	ds_write_b128 v137, v[22:25] offset:8192
	ds_write_b128 v137, v[26:29] offset:16384
	ds_write_b128 v137, v[30:33] offset:24576
	s_waitcnt lgkmcnt(0)
	s_barrier
	s_cbranch_scc0 .LBB0_2530
	s_lshl_b32 s26, s26, 6
	s_addk_i32 s26, 0xc0
	v_add_u32_e32 v0, s26, v60
	v_ashrrev_i32_e32 v0, 6, v0
	v_lshl_add_u32 v0, v0, 2, 0
	v_add_u32_e32 v0, 0x19e10, v0
	ds_read_b32 v14, v0
	v_mov_b64_e32 v[22:23], s[2:3]
	s_waitcnt lgkmcnt(0)
	v_lshl_or_b32 v0, v14, 6, v38
	v_cmp_ne_u32_e32 vcc, s50, v0
	s_and_saveexec_b64 s[6:7], vcc
	s_cbranch_execz .LBB0_2509
	v_cmp_gt_i32_e32 vcc, s50, v0
	v_mov_b64_e32 v[22:23], 0
	s_and_saveexec_b64 s[8:9], vcc
	s_cbranch_execz .LBB0_2508
	v_ashrrev_i32_e32 v14, 1, v14
	v_lshlrev_b32_e32 v14, 2, v14
	v_add_u32_e32 v14, 0x1a800, v14
	ds_read_b32 v14, v14
	s_nop 0
	v_lshlrev_b32_e32 v0, 12, v0
	v_and_b32_e32 v0, 0x7f000, v0
	s_mov_b64 s[36:37], 0x800
	s_waitcnt lgkmcnt(0)
	v_ashrrev_i32_e32 v15, 31, v14
	v_lshlrev_b64 v[14:15], 19, v[14:15]
	v_lshl_add_u64 v[14:15], s[80:81], 0, v[14:15]
	v_lshl_add_u64 v[14:15], v[14:15], 0, v[0:1]
	v_lshl_add_u64 v[14:15], v[14:15], 0, s[20:21]
	v_lshl_add_u64 v[22:23], v[14:15], 0, s[36:37]

.LBB0_2511:
	s_or_b64 exec, exec, s[6:7]
	v_add_u32_e32 v0, s26, v66
	v_ashrrev_i32_e32 v0, 6, v0
	v_lshl_add_u32 v0, v0, 2, 0
	v_add_u32_e32 v0, 0x19e10, v0
	ds_read_b32 v22, v0
	v_mov_b64_e32 v[26:27], s[2:3]
	s_waitcnt lgkmcnt(0)
	v_lshl_or_b32 v0, v22, 6, v39
	v_cmp_ne_u32_e32 vcc, s50, v0
	s_and_saveexec_b64 s[6:7], vcc
	s_cbranch_execz .LBB0_2515
	v_cmp_gt_i32_e32 vcc, s50, v0
	v_mov_b64_e32 v[26:27], 0
	s_and_saveexec_b64 s[8:9], vcc
	s_cbranch_execz .LBB0_2514
	v_ashrrev_i32_e32 v22, 1, v22
	v_lshlrev_b32_e32 v22, 2, v22
	v_add_u32_e32 v22, 0x1a800, v22
	ds_read_b32 v22, v22
	s_nop 0
	v_lshlrev_b32_e32 v0, 12, v0
	v_and_b32_e32 v0, 0x7f000, v0
	s_mov_b64 s[36:37], 0x800
	s_waitcnt lgkmcnt(0)
	v_ashrrev_i32_e32 v23, 31, v22
	v_lshlrev_b64 v[22:23], 19, v[22:23]
	v_lshl_add_u64 v[22:23], s[80:81], 0, v[22:23]
	v_lshl_add_u64 v[22:23], v[22:23], 0, v[0:1]
	v_lshl_add_u64 v[22:23], v[22:23], 0, s[20:21]
	v_lshl_add_u64 v[26:27], v[22:23], 0, s[36:37]

.LBB0_2517:
	s_or_b64 exec, exec, s[6:7]
	v_add_u32_e32 v0, s26, v62
	v_ashrrev_i32_e32 v0, 6, v0
	v_lshl_add_u32 v0, v0, 2, 0
	v_add_u32_e32 v0, 0x19e10, v0
	ds_read_b32 v26, v0
	v_mov_b64_e32 v[30:31], s[2:3]
	s_waitcnt lgkmcnt(0)
	v_lshl_or_b32 v0, v26, 6, v40
	v_cmp_ne_u32_e32 vcc, s50, v0
	s_and_saveexec_b64 s[6:7], vcc
	s_cbranch_execz .LBB0_2521
	v_cmp_gt_i32_e32 vcc, s50, v0
	v_mov_b64_e32 v[30:31], 0
	s_and_saveexec_b64 s[8:9], vcc
	s_cbranch_execz .LBB0_2520
	v_ashrrev_i32_e32 v26, 1, v26
	v_lshlrev_b32_e32 v26, 2, v26
	v_add_u32_e32 v26, 0x1a800, v26
	ds_read_b32 v26, v26
	s_nop 0
	v_lshlrev_b32_e32 v0, 12, v0
	v_and_b32_e32 v0, 0x7f000, v0
	s_mov_b64 s[36:37], 0x800
	s_waitcnt lgkmcnt(0)
	v_ashrrev_i32_e32 v27, 31, v26
	v_lshlrev_b64 v[26:27], 19, v[26:27]
	v_lshl_add_u64 v[26:27], s[80:81], 0, v[26:27]
	v_lshl_add_u64 v[26:27], v[26:27], 0, v[0:1]
	v_lshl_add_u64 v[26:27], v[26:27], 0, s[20:21]
	v_lshl_add_u64 v[30:31], v[26:27], 0, s[36:37]

.LBB0_2523:
	s_or_b64 exec, exec, s[6:7]
	v_add_u32_e32 v0, s26, v64
	v_ashrrev_i32_e32 v0, 6, v0
	v_lshl_add_u32 v0, v0, 2, 0
	v_add_u32_e32 v0, 0x19e10, v0
	ds_read_b32 v30, v0
	v_mov_b64_e32 v[34:35], s[2:3]
	s_waitcnt lgkmcnt(0)
	v_lshl_or_b32 v0, v30, 6, v41
	v_cmp_ne_u32_e32 vcc, s50, v0
	s_and_saveexec_b64 s[6:7], vcc
	s_cbranch_execz .LBB0_2527
	v_cmp_gt_i32_e32 vcc, s50, v0
	v_mov_b64_e32 v[34:35], 0
	s_and_saveexec_b64 s[8:9], vcc
	s_cbranch_execz .LBB0_2526
	v_ashrrev_i32_e32 v30, 1, v30
	v_lshlrev_b32_e32 v30, 2, v30
	v_add_u32_e32 v30, 0x1a800, v30
	ds_read_b32 v30, v30
	s_nop 0
	v_lshlrev_b32_e32 v0, 12, v0
	v_and_b32_e32 v0, 0x7f000, v0
	s_mov_b64 s[26:27], 0x800
	s_waitcnt lgkmcnt(0)
	v_ashrrev_i32_e32 v31, 31, v30
	v_lshlrev_b64 v[30:31], 19, v[30:31]
	v_lshl_add_u64 v[30:31], s[80:81], 0, v[30:31]
	v_lshl_add_u64 v[30:31], v[30:31], 0, v[0:1]
	v_lshl_add_u64 v[30:31], v[30:31], 0, s[20:21]
	v_lshl_add_u64 v[34:35], v[30:31], 0, s[26:27]

	.amdhsa_kernel _Z3fwd4Args
		.amdhsa_group_segment_fixed_size 0
		.amdhsa_private_segment_fixed_size 0
		.amdhsa_kernarg_size 520
		.amdhsa_user_sgpr_count 2
		.amdhsa_user_sgpr_dispatch_ptr 0
		.amdhsa_user_sgpr_queue_ptr 0
		.amdhsa_user_sgpr_kernarg_segment_ptr 1
		.amdhsa_user_sgpr_dispatch_id 0
		.amdhsa_user_sgpr_kernarg_preload_length 0
		.amdhsa_user_sgpr_kernarg_preload_offset 0
		.amdhsa_user_sgpr_private_segment_size 0
		.amdhsa_uses_dynamic_stack 0
		.amdhsa_enable_private_segment 0
		.amdhsa_system_sgpr_workgroup_id_x 1
		.amdhsa_system_sgpr_workgroup_id_y 0
		.amdhsa_system_sgpr_workgroup_id_z 0
		.amdhsa_system_sgpr_workgroup_info 0
		.amdhsa_system_vgpr_workitem_id 0
		.amdhsa_next_free_vgpr 256
		.amdhsa_next_free_sgpr 102
		.amdhsa_accum_offset 256
		.amdhsa_reserve_vcc 1
		.amdhsa_float_round_mode_32 0
		.amdhsa_float_round_mode_16_64 0
		.amdhsa_float_denorm_mode_32 3
		.amdhsa_float_denorm_mode_16_64 3
		.amdhsa_dx10_clamp 1
		.amdhsa_ieee_mode 1
		.amdhsa_fp16_overflow 0
		.amdhsa_tg_split 0
		.amdhsa_exception_fp_ieee_invalid_op 0
		.amdhsa_exception_fp_denorm_src 0
		.amdhsa_exception_fp_ieee_div_zero 0
		.amdhsa_exception_fp_ieee_overflow 0
		.amdhsa_exception_fp_ieee_underflow 0
		.amdhsa_exception_fp_ieee_inexact 0
		.amdhsa_exception_int_div_zero 0
	.end_amdhsa_kernel

amdhsa.kernels:
  - .agpr_count:     0
    .args:
      - .offset:         0
        .size:           264
        .value_kind:     by_value
      - .offset:         264
        .size:           4
        .value_kind:     hidden_block_count_x
      - .offset:         268
        .size:           4
        .value_kind:     hidden_block_count_y
      - .offset:         272
        .size:           4
        .value_kind:     hidden_block_count_z
      - .offset:         276
        .size:           2
        .value_kind:     hidden_group_size_x
      - .offset:         278
        .size:           2
        .value_kind:     hidden_group_size_y
      - .offset:         280
        .size:           2
        .value_kind:     hidden_group_size_z
      - .offset:         282
        .size:           2
        .value_kind:     hidden_remainder_x
      - .offset:         284
        .size:           2
        .value_kind:     hidden_remainder_y
      - .offset:         286
        .size:           2
        .value_kind:     hidden_remainder_z
      - .offset:         304
        .size:           8
        .value_kind:     hidden_global_offset_x
      - .offset:         312
        .size:           8
        .value_kind:     hidden_global_offset_y
      - .offset:         320
        .size:           8
        .value_kind:     hidden_global_offset_z
      - .offset:         328
        .size:           2
        .value_kind:     hidden_grid_dims
      - .offset:         384
        .size:           4
        .value_kind:     hidden_dynamic_lds_size
    .group_segment_fixed_size: 0
    .kernarg_segment_align: 8
    .kernarg_segment_size: 520
    .language:       OpenCL C
    .language_version:
      - 2
      - 0
    .max_flat_workgroup_size: 512
    .name:           _Z3fwd4Args
    .private_segment_fixed_size: 0
    .sgpr_count:     108
    .sgpr_spill_count: 240
    .symbol:         _Z3fwd4Args.kd
    .uniform_work_group_size: 1
    .uses_dynamic_stack: false
    .vgpr_count:     256
    .vgpr_spill_count: 0
    .wavefront_size: 64
